# SO12: scan chain prologue - the first block's raw-row DMA uses the SO1 piece descriptors (computed there, moved up from the loop pre-header) instead of hipcc's per-piece pointer-select loop (on SO7)
# speedup vs baseline: 1.0006x; 1.0006x over previous
.LBB0_357:
	v_readlane_b32 s10, v255, 49
	v_readlane_b32 s11, v255, 50
	s_and_b64 s[8:9], s[10:11], exec
	s_movk_i32 s3, 0x1000
	s_cselect_b32 s74, s3, 0x100
	s_lshl_b32 s81, s80, 12
	s_add_i32 s3, s81, 0x1000
	s_lshl_b32 s5, s80, 8
	s_and_b64 s[8:9], s[10:11], exec
	s_cselect_b32 s48, s3, s5
	s_cmp_eq_u32 s2, 1
	s_cselect_b64 s[12:13], -1, 0
	s_and_b64 s[8:9], s[12:13], exec
	s_cselect_b32 s49, 32, 0
	s_cmp_lg_u32 s30, 0
	s_cselect_b64 s[78:79], -1, 0
	s_lshl_b32 s31, s49, 6
	s_sub_i32 s45, s74, 64
	s_sub_i32 s3, s45, s31
	s_cmp_eq_u32 s30, 0
	s_cselect_b64 s[8:9], -1, 0
	s_and_b64 s[10:11], s[8:9], exec
	s_cselect_b32 s3, s31, s3
	s_cmpk_lt_u32 s0, 0xa80
	v_writelane_b32 v255, s5, 56
	s_cselect_b64 s[10:11], -1, 0
	v_writelane_b32 v255, s10, 57
	v_mov_b32_e32 v34, v1
	s_cmpk_gt_u32 s0, 0xa7f
	v_writelane_b32 v255, s11, 58
	s_cbranch_scc1 .LBB0_378
	s_add_i32 s5, s3, -1
	s_add_i32 s7, s74, -1
	s_lshl_b32 s10, s30, 7
	s_add_u32 s10, s54, s10
	s_addc_u32 s11, s55, 0
	s_lshl_b32 s18, s56, 7
	s_add_u32 s14, s36, s18
	s_addc_u32 s15, s37, 0
	s_add_u32 s16, s52, s18
	s_addc_u32 s17, s53, 0
	s_add_u32 s18, s42, s18
	s_addc_u32 s19, s43, 0
	s_lshl_b32 s20, s1, 3
	v_lshrrev_b32_e32 v34, 3, v1
	v_and_b32_e32 v35, 7, v1
	v_lshlrev_b32_e32 v35, 4, v35
	v_add_u32_e32 v34, s20, v34
	v_mov_b32_e32 v36, s18
	v_mov_b32_e32 v37, s19
	v_mov_b32_e32 v38, s16
	v_mov_b32_e32 v39, s17
	v_mov_b32_e32 v40, s14
	v_mov_b32_e32 v41, s15
	v_mov_b32_e32 v42, s10
	v_mov_b32_e32 v43, s11
	v_lshl_add_u64 v[44:45], v[42:43], 0, s[68:69]
	v_mov_b32_e32 v49, 0x800
	v_mov_b32_e32 v50, 0x200
	v_mov_b32_e32 v46, v34
	v_min_i32_e32 v46, 0x149, v46
	v_mul_hi_i32 v47, v46, s6
	v_ashrrev_i32_e32 v47, 1, v47
	v_mul_u32_u24_e32 v48, 5, v47
	v_sub_u32_e32 v48, v46, v48
	v_mov_b32_e32 v226, v47
	v_cmp_gt_u32_e32 vcc, 3, v48
	v_mov_b32_e32 v51, v36
	v_mov_b32_e32 v52, v37
	v_cndmask_b32_e32 v227, v50, v49, vcc
	v_cmp_eq_u32_e32 vcc, 1, v48
	s_nop 1
	v_cndmask_b32_e32 v51, v51, v38, vcc
	v_cndmask_b32_e32 v52, v52, v39, vcc
	v_cmp_eq_u32_e32 vcc, 2, v48
	s_nop 1
	v_cndmask_b32_e32 v51, v51, v40, vcc
	v_cndmask_b32_e32 v52, v52, v41, vcc
	v_cmp_eq_u32_e32 vcc, 3, v48
	s_nop 1
	v_cndmask_b32_e32 v51, v51, v42, vcc
	v_cndmask_b32_e32 v52, v52, v43, vcc
	v_cmp_eq_u32_e32 vcc, 4, v48
	s_nop 1
	v_cndmask_b32_e32 v51, v51, v44, vcc
	v_cndmask_b32_e32 v52, v52, v45, vcc
	v_mul_lo_u32 v53, s48, v227
	v_add_u32_e32 v53, v53, v35
	v_add_co_u32_e32 v228, vcc, v51, v53
	s_nop 1
	v_addc_co_u32_e32 v229, vcc, 0, v52, vcc
	v_add_u32_e32 v46, 64, v34
	v_min_i32_e32 v46, 0x149, v46
	v_mul_hi_i32 v47, v46, s6
	v_ashrrev_i32_e32 v47, 1, v47
	v_mul_u32_u24_e32 v48, 5, v47
	v_sub_u32_e32 v48, v46, v48
	v_mov_b32_e32 v230, v47
	v_cmp_gt_u32_e32 vcc, 3, v48
	v_mov_b32_e32 v51, v36
	v_mov_b32_e32 v52, v37
	v_cndmask_b32_e32 v231, v50, v49, vcc
	v_cmp_eq_u32_e32 vcc, 1, v48
	s_nop 1
	v_cndmask_b32_e32 v51, v51, v38, vcc
	v_cndmask_b32_e32 v52, v52, v39, vcc
	v_cmp_eq_u32_e32 vcc, 2, v48
	s_nop 1
	v_cndmask_b32_e32 v51, v51, v40, vcc
	v_cndmask_b32_e32 v52, v52, v41, vcc
	v_cmp_eq_u32_e32 vcc, 3, v48
	s_nop 1
	v_cndmask_b32_e32 v51, v51, v42, vcc
	v_cndmask_b32_e32 v52, v52, v43, vcc
	v_cmp_eq_u32_e32 vcc, 4, v48
	s_nop 1
	v_cndmask_b32_e32 v51, v51, v44, vcc
	v_cndmask_b32_e32 v52, v52, v45, vcc
	v_mul_lo_u32 v53, s48, v231
	v_add_u32_e32 v53, v53, v35
	v_add_co_u32_e32 v232, vcc, v51, v53
	s_nop 1
	v_addc_co_u32_e32 v233, vcc, 0, v52, vcc
	v_add_u32_e32 v46, 128, v34
	v_min_i32_e32 v46, 0x149, v46
	v_mul_hi_i32 v47, v46, s6
	v_ashrrev_i32_e32 v47, 1, v47
	v_mul_u32_u24_e32 v48, 5, v47
	v_sub_u32_e32 v48, v46, v48
	v_mov_b32_e32 v234, v47
	v_cmp_gt_u32_e32 vcc, 3, v48
	v_mov_b32_e32 v51, v36
	v_mov_b32_e32 v52, v37
	v_cndmask_b32_e32 v235, v50, v49, vcc
	v_cmp_eq_u32_e32 vcc, 1, v48
	s_nop 1
	v_cndmask_b32_e32 v51, v51, v38, vcc
	v_cndmask_b32_e32 v52, v52, v39, vcc
	v_cmp_eq_u32_e32 vcc, 2, v48
	s_nop 1
	v_cndmask_b32_e32 v51, v51, v40, vcc
	v_cndmask_b32_e32 v52, v52, v41, vcc
	v_cmp_eq_u32_e32 vcc, 3, v48
	s_nop 1
	v_cndmask_b32_e32 v51, v51, v42, vcc
	v_cndmask_b32_e32 v52, v52, v43, vcc
	v_cmp_eq_u32_e32 vcc, 4, v48
	s_nop 1
	v_cndmask_b32_e32 v51, v51, v44, vcc
	v_cndmask_b32_e32 v52, v52, v45, vcc
	v_mul_lo_u32 v53, s48, v235
	v_add_u32_e32 v53, v53, v35
	v_add_co_u32_e32 v236, vcc, v51, v53
	s_nop 1
	v_addc_co_u32_e32 v237, vcc, 0, v52, vcc
	v_add_u32_e32 v46, 192, v34
	v_min_i32_e32 v46, 0x149, v46
	v_mul_hi_i32 v47, v46, s6
	v_ashrrev_i32_e32 v47, 1, v47
	v_mul_u32_u24_e32 v48, 5, v47
	v_sub_u32_e32 v48, v46, v48
	v_mov_b32_e32 v238, v47
	v_cmp_gt_u32_e32 vcc, 3, v48
	v_mov_b32_e32 v51, v36
	v_mov_b32_e32 v52, v37
	v_cndmask_b32_e32 v239, v50, v49, vcc
	v_cmp_eq_u32_e32 vcc, 1, v48
	s_nop 1
	v_cndmask_b32_e32 v51, v51, v38, vcc
	v_cndmask_b32_e32 v52, v52, v39, vcc
	v_cmp_eq_u32_e32 vcc, 2, v48
	s_nop 1
	v_cndmask_b32_e32 v51, v51, v40, vcc
	v_cndmask_b32_e32 v52, v52, v41, vcc
	v_cmp_eq_u32_e32 vcc, 3, v48
	s_nop 1
	v_cndmask_b32_e32 v51, v51, v42, vcc
	v_cndmask_b32_e32 v52, v52, v43, vcc
	v_cmp_eq_u32_e32 vcc, 4, v48
	s_nop 1
	v_cndmask_b32_e32 v51, v51, v44, vcc
	v_cndmask_b32_e32 v52, v52, v45, vcc
	v_mul_lo_u32 v53, s48, v239
	v_add_u32_e32 v53, v53, v35
	v_add_co_u32_e32 v240, vcc, v51, v53
	s_nop 1
	v_addc_co_u32_e32 v241, vcc, 0, v52, vcc
	v_add_u32_e32 v46, 256, v34
	v_min_i32_e32 v46, 0x149, v46
	v_mul_hi_i32 v47, v46, s6
	v_ashrrev_i32_e32 v47, 1, v47
	v_mul_u32_u24_e32 v48, 5, v47
	v_sub_u32_e32 v48, v46, v48
	v_mov_b32_e32 v242, v47
	v_cmp_gt_u32_e32 vcc, 3, v48
	v_mov_b32_e32 v51, v36
	v_mov_b32_e32 v52, v37
	v_cndmask_b32_e32 v243, v50, v49, vcc
	v_cmp_eq_u32_e32 vcc, 1, v48
	s_nop 1
	v_cndmask_b32_e32 v51, v51, v38, vcc
	v_cndmask_b32_e32 v52, v52, v39, vcc
	v_cmp_eq_u32_e32 vcc, 2, v48
	s_nop 1
	v_cndmask_b32_e32 v51, v51, v40, vcc
	v_cndmask_b32_e32 v52, v52, v41, vcc
	v_cmp_eq_u32_e32 vcc, 3, v48
	s_nop 1
	v_cndmask_b32_e32 v51, v51, v42, vcc
	v_cndmask_b32_e32 v52, v52, v43, vcc
	v_cmp_eq_u32_e32 vcc, 4, v48
	s_nop 1
	v_cndmask_b32_e32 v51, v51, v44, vcc
	v_cndmask_b32_e32 v52, v52, v45, vcc
	v_mul_lo_u32 v53, s48, v243
	v_add_u32_e32 v53, v53, v35
	v_add_co_u32_e32 v244, vcc, v51, v53
	s_nop 1
	v_addc_co_u32_e32 v245, vcc, 0, v52, vcc
	v_add_u32_e32 v46, 320, v34
	v_min_i32_e32 v46, 0x149, v46
	v_mul_hi_i32 v47, v46, s6
	v_ashrrev_i32_e32 v47, 1, v47
	v_mul_u32_u24_e32 v48, 5, v47
	v_sub_u32_e32 v48, v46, v48
	v_mov_b32_e32 v246, v47
	v_cmp_gt_u32_e32 vcc, 3, v48
	v_mov_b32_e32 v51, v36
	v_mov_b32_e32 v52, v37
	v_cndmask_b32_e32 v247, v50, v49, vcc
	v_cmp_eq_u32_e32 vcc, 1, v48
	s_nop 1
	v_cndmask_b32_e32 v51, v51, v38, vcc
	v_cndmask_b32_e32 v52, v52, v39, vcc
	v_cmp_eq_u32_e32 vcc, 2, v48
	s_nop 1
	v_cndmask_b32_e32 v51, v51, v40, vcc
	v_cndmask_b32_e32 v52, v52, v41, vcc
	v_cmp_eq_u32_e32 vcc, 3, v48
	s_nop 1
	v_cndmask_b32_e32 v51, v51, v42, vcc
	v_cndmask_b32_e32 v52, v52, v43, vcc
	v_cmp_eq_u32_e32 vcc, 4, v48
	s_nop 1
	v_cndmask_b32_e32 v51, v51, v44, vcc
	v_cndmask_b32_e32 v52, v52, v45, vcc
	v_mul_lo_u32 v53, s48, v247
	v_add_u32_e32 v53, v53, v35
	v_add_co_u32_e32 v248, vcc, v51, v53
	s_nop 1
	v_addc_co_u32_e32 v249, vcc, 0, v52, vcc
	s_lshl_b32 s20, s1, 10
	s_add_i32 s20, s20, 0x8800
	v_add_u32_e32 v250, s5, v226
	v_med3_i32 v250, v250, 0, s7
	v_mad_u64_u32 v[252:253], vcc, v250, v227, v[228:229]
	s_mov_b32 s21, m0
	s_mov_b32 m0, s20
	s_nop 0
	global_load_lds_dwordx4 v[252:253], off
	s_mov_b32 m0, s21
	s_add_i32 s20, s20, 0x2000
	v_add_u32_e32 v250, s5, v230
	v_med3_i32 v250, v250, 0, s7
	v_mad_u64_u32 v[252:253], vcc, v250, v231, v[232:233]
	s_mov_b32 s21, m0
	s_mov_b32 m0, s20
	s_nop 0
	global_load_lds_dwordx4 v[252:253], off
	s_mov_b32 m0, s21
	s_add_i32 s20, s20, 0x2000
	v_add_u32_e32 v250, s5, v234
	v_med3_i32 v250, v250, 0, s7
	v_mad_u64_u32 v[252:253], vcc, v250, v235, v[236:237]
	s_mov_b32 s21, m0
	s_mov_b32 m0, s20
	s_nop 0
	global_load_lds_dwordx4 v[252:253], off
	s_mov_b32 m0, s21
	s_add_i32 s20, s20, 0x2000
	v_add_u32_e32 v250, s5, v238
	v_med3_i32 v250, v250, 0, s7
	v_mad_u64_u32 v[252:253], vcc, v250, v239, v[240:241]
	s_mov_b32 s21, m0
	s_mov_b32 m0, s20
	s_nop 0
	global_load_lds_dwordx4 v[252:253], off
	s_mov_b32 m0, s21
	s_add_i32 s20, s20, 0x2000
	v_add_u32_e32 v250, s5, v242
	v_med3_i32 v250, v250, 0, s7
	v_mad_u64_u32 v[252:253], vcc, v250, v243, v[244:245]
	s_mov_b32 s21, m0
	s_mov_b32 m0, s20
	s_nop 0
	global_load_lds_dwordx4 v[252:253], off
	s_mov_b32 m0, s21
	s_add_i32 s20, s20, 0x2000
	s_cmp_gt_u32 s1, 1
	s_cbranch_scc1 .Lso12_skip5
	v_add_u32_e32 v250, s5, v246
	v_med3_i32 v250, v250, 0, s7
	v_mad_u64_u32 v[252:253], vcc, v250, v247, v[248:249]
	s_mov_b32 s21, m0
	s_mov_b32 m0, s20
	s_nop 0
	global_load_lds_dwordx4 v[252:253], off
	s_mov_b32 m0, s21
	s_add_i32 s20, s20, 0x2000
.Lso12_skip5:
.LBB0_378:
	s_waitcnt vmcnt(0)
	s_cmpk_lt_u32 s0, 0x100
	s_cselect_b64 s[82:83], -1, 0
	s_cmpk_gt_u32 s0, 0xff
	s_waitcnt lgkmcnt(0)
	s_barrier
	s_cbranch_scc0 .LBB0_380
	v_mov_b32_e32 v98, v1
	v_readlane_b32 s10, v255, 25
	v_lshlrev_b32_e32 v34, 7, v98
	v_ashrrev_i32_e32 v36, 1, v98
	v_and_b32_e32 v106, 0x780, v34
	v_readlane_b32 s11, v255, 26
	v_and_b32_e32 v36, -8, v36
	v_ashrrev_i32_e32 v37, 31, v36
	v_lshl_add_u64 v[34:35], s[10:11], 0, v[106:107]
	s_lshl_b32 s5, s30, 17
	s_lshl_b32 s7, s56, 13
	v_lshl_add_u64 v[34:35], v[36:37], 1, v[34:35]
	s_or_b32 s40, s7, s5
	v_lshl_add_u64 v[34:35], v[34:35], 0, s[40:41]
	s_movk_i32 s5, 0x1000
	v_add_co_u32_e32 v36, vcc, s5, v34
	s_mov_b32 s5, 0x40000
	s_nop 0
	v_addc_co_u32_e32 v37, vcc, 0, v35, vcc
	v_add_co_u32_e32 v42, vcc, s5, v34
	s_add_i32 s16, s1, -4
	s_nop 0
	v_addc_co_u32_e32 v43, vcc, 0, v35, vcc
	s_mov_b32 s5, 0x41000
	v_add_co_u32_e32 v86, vcc, s5, v34
	s_lshl_b32 s5, s16, 4
	s_add_i32 s17, s31, s5
	s_xor_b32 s10, s17, -8
	s_add_i32 s7, 0, 0x22000
	s_lshl_b32 s15, s16, 1
	s_add_i32 s14, s74, -1
	s_add_i32 s18, s10, s74
	s_and_b64 s[10:11], s[8:9], exec
	v_and_b32_e32 v78, 7, v98
	v_ashrrev_i32_e32 v89, 3, v98
	s_cselect_b32 s10, s17, s18
	v_lshlrev_b32_e32 v106, 4, v78
	v_add_u32_e32 v94, s10, v89
	v_lshl_add_u32 v99, v78, 5, s7
	v_sub_u32_e32 v79, 7, v89
	v_add_u32_e32 v88, 0, v106
	v_subrev_u32_e32 v78, s3, v94
	v_cndmask_b32_e64 v79, v79, v89, s[8:9]
	v_mad_u64_u32 v[100:101], s[10:11], v78, s58, v[88:89]
	global_load_dwordx4 v[66:69], v[34:35], off
	global_load_dwordx4 v[54:57], v[34:35], off offset:64
	global_load_dwordx4 v[58:61], v[34:35], off offset:2048
	global_load_dwordx4 v[62:65], v[34:35], off offset:2112
	global_load_dwordx4 v[74:77], v[36:37], off
	global_load_dwordx4 v[70:73], v[36:37], off offset:64
	global_load_dwordx4 v[50:53], v[36:37], off offset:2048
	global_load_dwordx4 v[46:49], v[36:37], off offset:2112
	v_addc_co_u32_e32 v87, vcc, 0, v35, vcc
	global_load_dwordx4 v[34:37], v[42:43], off offset:64
	global_load_dwordx4 v[38:41], v[42:43], off offset:2048
	s_nop 0
	global_load_dwordx4 v[42:45], v[42:43], off offset:2112
	v_lshlrev_b32_e32 v125, 7, v79
	ds_read_b128 v[78:81], v100 offset:35200
	ds_read_b128 v[82:85], v100 offset:35840
	ds_read_b128 v[90:93], v100 offset:36480
	s_lshl_b32 s10, s16, 11
	s_add_i32 s10, s10, 0
	v_add3_u32 v127, s10, v125, v106
	v_cmp_lt_i32_e64 s[10:11], 0, v94
	v_cmp_gt_i32_e32 vcc, s14, v94
	s_waitcnt lgkmcnt(1)
	v_and_b32_e32 v132, 0xffff0000, v82
	v_cndmask_b32_e64 v96, 0, v81, s[10:11]
	v_cndmask_b32_e64 v97, 0, v80, s[10:11]
	v_cndmask_b32_e64 v101, 0, v79, s[10:11]
	v_cndmask_b32_e64 v128, 0, v78, s[10:11]
	ds_read_b128 v[78:81], v99 offset:768
	s_waitcnt lgkmcnt(1)
	v_cndmask_b32_e32 v90, 0, v90, vcc
	v_cndmask_b32_e32 v130, 0, v93, vcc
	v_cndmask_b32_e32 v131, 0, v92, vcc
	v_and_b32_e32 v92, 0xffff0000, v90
	v_and_b32_e32 v93, 0xffff0000, v128
	v_lshlrev_b32_e32 v128, 16, v128
	v_lshlrev_b32_e32 v90, 16, v90
	v_add_f32_e32 v92, v92, v93
	v_add_f32_e32 v90, v90, v128
	v_lshlrev_b32_e32 v82, 16, v82
	v_fma_f32 v133, v92, 0.5, -v132
	v_fma_f32 v90, v90, 0.5, -v82
	ds_read_b128 v[92:95], v99 offset:784
	s_waitcnt lgkmcnt(1)
	v_fmac_f32_e32 v132, v79, v133
	v_fmac_f32_e32 v82, v78, v90
	v_add_f32_e32 v79, v132, v132
	v_add_f32_e32 v78, v82, v82
	v_mul_f32_e32 v79, 0x3fb8aa3b, v79
	v_mul_f32_e32 v78, 0x3fb8aa3b, v78
	v_exp_f32_e32 v79, v79
	v_exp_f32_e32 v82, v78
	v_cndmask_b32_e32 v90, 0, v91, vcc
	v_and_b32_e32 v91, 0xffff0000, v101
	v_add_f32_e32 v78, 1.0, v79
	v_add_f32_e32 v79, 1.0, v82
	v_and_b32_e32 v82, 0xffff0000, v90
	v_add_f32_e32 v82, v82, v91
	v_and_b32_e32 v91, 0xffff0000, v83
	v_fma_f32 v82, v82, 0.5, -v91
	v_fmac_f32_e32 v91, v81, v82
	v_lshlrev_b32_e32 v82, 16, v101
	v_lshlrev_b32_e32 v90, 16, v90
	v_add_f32_e32 v82, v90, v82
	v_lshlrev_b32_e32 v83, 16, v83
	v_fma_f32 v82, v82, 0.5, -v83
	v_fmac_f32_e32 v83, v80, v82
	v_add_f32_e32 v81, v91, v91
	v_add_f32_e32 v80, v83, v83
	v_mul_f32_e32 v81, 0x3fb8aa3b, v81
	v_mul_f32_e32 v80, 0x3fb8aa3b, v80
	v_exp_f32_e32 v81, v81
	v_exp_f32_e32 v82, v80
	v_rcp_f32_e32 v80, v79
	v_and_b32_e32 v83, 0xffff0000, v97
	v_add_f32_e32 v79, 1.0, v81
	v_add_f32_e32 v81, 1.0, v82
	v_and_b32_e32 v82, 0xffff0000, v131
	v_add_f32_e32 v82, v82, v83
	v_and_b32_e32 v83, 0xffff0000, v84
	v_fma_f32 v82, v82, 0.5, -v83
	s_waitcnt lgkmcnt(0)
	v_fmac_f32_e32 v83, v93, v82
	v_add_f32_e32 v82, v83, v83
	v_lshlrev_b32_e32 v83, 16, v97
	v_lshlrev_b32_e32 v90, 16, v131
	v_add_f32_e32 v83, v90, v83
	v_lshlrev_b32_e32 v84, 16, v84
	v_fma_f32 v83, v83, 0.5, -v84
	v_fmac_f32_e32 v84, v92, v83
	v_add_f32_e32 v83, v84, v84
	v_and_b32_e32 v84, 0xffff0000, v130
	v_and_b32_e32 v90, 0xffff0000, v96
	v_add_f32_e32 v84, v84, v90
	v_and_b32_e32 v90, 0xffff0000, v85
	v_fma_f32 v84, v84, 0.5, -v90
	v_fmac_f32_e32 v90, v84, v95
	v_add_f32_e32 v84, v90, v90
	v_mul_f32_e32 v84, 0x3fb8aa3b, v84
	v_exp_f32_e32 v90, v84
	v_lshlrev_b32_e32 v84, 16, v96
	v_lshlrev_b32_e32 v91, 16, v130
	v_add_f32_e32 v84, v91, v84
	v_lshlrev_b32_e32 v85, 16, v85
	v_fma_f32 v84, v84, 0.5, -v85
	v_fmac_f32_e32 v85, v84, v94
	v_add_f32_e32 v84, v85, v85
	v_mul_f32_e32 v83, 0x3fb8aa3b, v83
	v_mul_f32_e32 v84, 0x3fb8aa3b, v84
	v_exp_f32_e32 v83, v83
	v_exp_f32_e32 v85, v84
	v_mul_f32_e32 v82, 0x3fb8aa3b, v82
	v_exp_f32_e32 v82, v82
	v_add_f32_e32 v83, 1.0, v83
	v_add_f32_e32 v85, 1.0, v85
	v_rcp_f32_e32 v81, v81
	v_rcp_f32_e32 v84, v83
	v_rcp_f32_e32 v85, v85
	v_add_f32_e32 v82, 1.0, v82
	v_add_f32_e32 v83, 1.0, v90
	v_rcp_f32_e32 v78, v78
	v_rcp_f32_e32 v79, v79
	v_rcp_f32_e32 v82, v82
	v_rcp_f32_e32 v83, v83
	v_pk_fma_f32 v[80:81], v[80:81], 2.0, 1.0 op_sel_hi:[1,0,0] neg_lo:[1,0,0] neg_hi:[1,0,0]
	v_pk_fma_f32 v[84:85], v[84:85], 2.0, 1.0 op_sel_hi:[1,0,0] neg_lo:[1,0,0] neg_hi:[1,0,0]
	v_bfe_u32 v90, v80, 16, 1
	v_bfe_u32 v91, v81, 16, 1
	v_bfe_u32 v92, v84, 16, 1
	v_pk_fma_f32 v[78:79], v[78:79], 2.0, 1.0 op_sel_hi:[1,0,0] neg_lo:[1,0,0] neg_hi:[1,0,0]
	v_pk_fma_f32 v[82:83], v[82:83], 2.0, 1.0 op_sel_hi:[1,0,0] neg_lo:[1,0,0] neg_hi:[1,0,0]
	v_add3_u32 v84, v84, v92, s46
	v_add3_u32 v81, v81, v91, s46
	v_add3_u32 v80, v80, v90, s46
	v_lshrrev_b32_e32 v90, 16, v80
	v_lshrrev_b32_e32 v91, 16, v81
	v_lshrrev_b32_e32 v80, 16, v84
	v_cvt_pk_bf16_f32 v81, v85, v83
	v_bfe_u32 v85, v82, 16, 1
	v_bfe_u32 v92, v79, 16, 1
	v_bfe_u32 v93, v78, 16, 1
	v_add3_u32 v78, v78, v93, s46
	v_add3_u32 v79, v79, v92, s46
	v_add3_u32 v82, v82, v85, s46
	s_mov_b32 s18, 0xffff0000
	v_and_or_b32 v80, v82, s18, v80
	v_and_or_b32 v79, v79, s18, v91
	v_and_or_b32 v78, v78, s18, v90
	ds_write_b128 v127, v[78:81] offset:16384
	ds_read_b128 v[90:93], v100 offset:35328
	global_load_dwordx4 v[82:85], v[86:87], off offset:-4096
	global_load_dwordx4 v[78:81], v[86:87], off
	ds_read_b128 v[94:97], v100 offset:35968
	ds_read_b128 v[130:133], v100 offset:36608
	s_or_b32 s15, s15, 1
	s_waitcnt lgkmcnt(2)
	v_cndmask_b32_e64 v128, 0, v92, s[10:11]
	v_cndmask_b32_e64 v100, 0, v91, s[10:11]
	v_cndmask_b32_e64 v138, 0, v90, s[10:11]
	v_cndmask_b32_e64 v139, 0, v93, s[10:11]
	ds_read_b128 v[90:93], v99 offset:1024
	ds_read_b128 v[134:137], v99 offset:1040
	s_waitcnt lgkmcnt(2)
	v_cndmask_b32_e32 v149, 0, v131, vcc
	v_cndmask_b32_e32 v130, 0, v130, vcc
	v_lshlrev_b32_e32 v142, 16, v138
	v_lshlrev_b32_e32 v144, 16, v130
	v_lshlrev_b32_e32 v143, 16, v100
	v_lshlrev_b32_e32 v145, 16, v149
	v_pk_add_f32 v[142:143], v[142:143], v[144:145]
	v_lshlrev_b32_e32 v145, 16, v95
	v_lshlrev_b32_e32 v144, 16, v94
	v_pk_fma_f32 v[142:143], v[142:143], 0.5, v[144:145] op_sel_hi:[1,0,1] neg_lo:[0,0,1] neg_hi:[0,0,1]
	s_waitcnt lgkmcnt(1)
	v_mov_b32_e32 v150, v90
	v_mov_b32_e32 v151, v92
	v_pk_fma_f32 v[142:143], v[150:151], v[142:143], v[144:145]
	v_and_b32_e32 v146, 0xffff0000, v138
	v_and_b32_e32 v148, 0xffff0000, v130
	v_and_b32_e32 v147, 0xffff0000, v100
	v_and_b32_e32 v149, 0xffff0000, v149
	v_and_b32_sdwa v90, v143, v213 dst_sel:DWORD dst_unused:UNUSED_PAD src0_sel:WORD_1 src1_sel:DWORD
	v_and_b32_sdwa v92, v142, v213 dst_sel:DWORD dst_unused:UNUSED_PAD src0_sel:WORD_1 src1_sel:DWORD
	v_add3_u32 v100, v142, v92, s46
	v_add3_u32 v130, v143, v90, s46
	v_pk_add_f32 v[142:143], v[146:147], v[148:149]
	v_and_b32_e32 v95, 0xffff0000, v95
	v_and_b32_e32 v94, 0xffff0000, v94
	v_pk_fma_f32 v[142:143], v[142:143], 0.5, v[94:95] op_sel_hi:[1,0,1] neg_lo:[0,0,1] neg_hi:[0,0,1]
	v_mov_b32_e32 v92, v91
	v_pk_fma_f32 v[90:91], v[92:93], v[142:143], v[94:95]
	v_cndmask_b32_e32 v140, 0, v132, vcc
	v_and_b32_sdwa v92, v91, v213 dst_sel:DWORD dst_unused:UNUSED_PAD src0_sel:WORD_1 src1_sel:DWORD
	v_and_b32_sdwa v93, v90, v213 dst_sel:DWORD dst_unused:UNUSED_PAD src0_sel:WORD_1 src1_sel:DWORD
	v_add3_u32 v91, v91, v92, s46
	v_add3_u32 v90, v90, v93, s46
	v_cndmask_b32_e32 v141, 0, v133, vcc
	v_and_b32_e32 v91, 0xffff0000, v91
	v_and_b32_e32 v90, 0xffff0000, v90
	v_and_b32_e32 v101, 0xffff0000, v139
	v_and_b32_e32 v131, 0xffff0000, v141
	v_or_b32_sdwa v91, v130, v91 dst_sel:DWORD dst_unused:UNUSED_PAD src0_sel:WORD_1 src1_sel:DWORD
	v_or_b32_sdwa v90, v100, v90 dst_sel:DWORD dst_unused:UNUSED_PAD src0_sel:WORD_1 src1_sel:DWORD
	v_lshlrev_b32_e32 v100, 16, v128
	v_lshlrev_b32_e32 v130, 16, v140
	v_pk_add_f32 v[92:93], v[100:101], v[130:131]
	v_lshlrev_b32_e32 v94, 16, v96
	v_and_b32_e32 v95, 0xffff0000, v97
	s_waitcnt lgkmcnt(0)
	v_mov_b32_e32 v132, v135
	v_lshlrev_b32_e32 v139, 16, v139
	v_lshlrev_b32_e32 v141, 16, v141
	v_and_b32_e32 v138, 0xffff0000, v128
	v_and_b32_e32 v140, 0xffff0000, v140
	v_pk_fma_f32 v[92:93], v[92:93], 0.5, v[94:95] op_sel_hi:[1,0,1] neg_lo:[0,0,1] neg_hi:[0,0,1]
	v_mov_b32_e32 v135, v137
	v_pk_fma_f32 v[92:93], v[92:93], v[134:135], v[94:95]
	v_pk_add_f32 v[94:95], v[138:139], v[140:141]
	v_and_b32_e32 v96, 0xffff0000, v96
	v_lshlrev_b32_e32 v97, 16, v97
	s_lshl_b32 s10, s15, 3
	v_mov_b32_e32 v133, v136
	v_pk_fma_f32 v[94:95], v[94:95], 0.5, v[96:97] op_sel_hi:[1,0,1] neg_lo:[0,0,1] neg_hi:[0,0,1]
	s_add_i32 s16, s10, s31
	v_pk_fma_f32 v[94:95], v[94:95], v[132:133], v[96:97]
	s_xor_b32 s10, s16, -8
	s_add_i32 s17, s10, s74
	s_and_b64 s[10:11], s[8:9], exec
	s_cselect_b32 s10, s16, s17
	v_add_u32_e32 v96, s10, v89
	v_cvt_pk_bf16_f32 v93, v95, v93
	v_cvt_pk_bf16_f32 v92, v92, v94
	v_subrev_u32_e32 v89, s3, v96
	ds_write_b128 v127, v[90:93] offset:24576
	v_mad_u64_u32 v[100:101], s[10:11], v89, s58, v[88:89]
	ds_read_b128 v[88:91], v100 offset:35200
	ds_read_b128 v[92:95], v100 offset:35840
	ds_read_b128 v[130:133], v100 offset:36480
	s_lshl_b32 s3, s15, 10
	s_add_i32 s3, s3, 0
	v_cmp_lt_i32_e64 s[10:11], 0, v96
	v_add3_u32 v106, s3, v125, v106
	v_cmp_gt_i32_e32 vcc, s14, v96
	s_waitcnt lgkmcnt(2)
	v_cndmask_b32_e64 v97, 0, v91, s[10:11]
	v_cndmask_b32_e64 v101, 0, v90, s[10:11]
	v_cndmask_b32_e64 v125, 0, v89, s[10:11]
	v_cndmask_b32_e64 v127, 0, v88, s[10:11]
	ds_read_b128 v[88:91], v99 offset:768
	s_waitcnt lgkmcnt(1)
	v_cndmask_b32_e32 v130, 0, v130, vcc
	v_cndmask_b32_e32 v96, 0, v133, vcc
	v_cndmask_b32_e32 v128, 0, v132, vcc
	v_and_b32_e32 v132, 0xffff0000, v130
	v_and_b32_e32 v133, 0xffff0000, v127
	v_lshlrev_b32_e32 v127, 16, v127
	v_lshlrev_b32_e32 v130, 16, v130
	v_add_f32_e32 v132, v132, v133
	v_and_b32_e32 v136, 0xffff0000, v92
	v_add_f32_e32 v127, v130, v127
	v_lshlrev_b32_e32 v92, 16, v92
	v_fma_f32 v137, v132, 0.5, -v136
	v_fma_f32 v127, v127, 0.5, -v92
	ds_read_b128 v[132:135], v99 offset:784
	s_waitcnt lgkmcnt(1)
	v_fmac_f32_e32 v136, v89, v137
	v_fmac_f32_e32 v92, v88, v127
	v_add_f32_e32 v89, v136, v136
	v_add_f32_e32 v88, v92, v92
	v_mul_f32_e32 v89, 0x3fb8aa3b, v89
	v_mul_f32_e32 v88, 0x3fb8aa3b, v88
	v_exp_f32_e32 v89, v89
	v_exp_f32_e32 v92, v88
	v_cndmask_b32_e32 v127, 0, v131, vcc
	v_and_b32_e32 v130, 0xffff0000, v125
	v_add_f32_e32 v88, 1.0, v89
	v_add_f32_e32 v89, 1.0, v92
	v_and_b32_e32 v92, 0xffff0000, v127
	v_add_f32_e32 v92, v92, v130
	v_and_b32_e32 v130, 0xffff0000, v93
	v_fma_f32 v92, v92, 0.5, -v130
	v_fmac_f32_e32 v130, v91, v92
	v_lshlrev_b32_e32 v92, 16, v125
	v_lshlrev_b32_e32 v125, 16, v127
	v_add_f32_e32 v92, v125, v92
	v_lshlrev_b32_e32 v93, 16, v93
	v_fma_f32 v92, v92, 0.5, -v93
	v_fmac_f32_e32 v93, v90, v92
	v_add_f32_e32 v91, v130, v130
	v_add_f32_e32 v90, v93, v93
	v_mul_f32_e32 v91, 0x3fb8aa3b, v91
	v_mul_f32_e32 v90, 0x3fb8aa3b, v90
	v_exp_f32_e32 v91, v91
	v_exp_f32_e32 v92, v90
	v_rcp_f32_e32 v90, v89
	v_and_b32_e32 v93, 0xffff0000, v101
	v_add_f32_e32 v89, 1.0, v91
	v_add_f32_e32 v91, 1.0, v92
	v_and_b32_e32 v92, 0xffff0000, v128
	v_add_f32_e32 v92, v92, v93
	v_and_b32_e32 v93, 0xffff0000, v94
	v_fma_f32 v92, v92, 0.5, -v93
	s_waitcnt lgkmcnt(0)
	v_fmac_f32_e32 v93, v133, v92
	v_add_f32_e32 v92, v93, v93
	v_lshlrev_b32_e32 v93, 16, v101
	v_lshlrev_b32_e32 v101, 16, v128
	v_add_f32_e32 v93, v101, v93
	v_lshlrev_b32_e32 v94, 16, v94
	v_fma_f32 v93, v93, 0.5, -v94
	v_fmac_f32_e32 v94, v132, v93
	v_add_f32_e32 v93, v94, v94
	v_and_b32_e32 v94, 0xffff0000, v96
	v_and_b32_e32 v101, 0xffff0000, v97
	v_add_f32_e32 v94, v94, v101
	v_and_b32_e32 v101, 0xffff0000, v95
	v_fma_f32 v94, v94, 0.5, -v101
	v_fmac_f32_e32 v101, v94, v135
	v_add_f32_e32 v94, v101, v101
	v_mul_f32_e32 v94, 0x3fb8aa3b, v94
	v_exp_f32_e32 v101, v94
	v_lshlrev_b32_e32 v94, 16, v97
	v_lshlrev_b32_e32 v96, 16, v96
	v_add_f32_e32 v94, v96, v94
	v_lshlrev_b32_e32 v95, 16, v95
	v_fma_f32 v94, v94, 0.5, -v95
	v_fmac_f32_e32 v95, v94, v134
	v_add_f32_e32 v94, v95, v95
	v_mul_f32_e32 v93, 0x3fb8aa3b, v93
	v_mul_f32_e32 v94, 0x3fb8aa3b, v94
	v_exp_f32_e32 v93, v93
	v_exp_f32_e32 v95, v94
	v_mul_f32_e32 v92, 0x3fb8aa3b, v92
	v_exp_f32_e32 v92, v92
	v_add_f32_e32 v93, 1.0, v93
	v_add_f32_e32 v95, 1.0, v95
	v_rcp_f32_e32 v91, v91
	v_rcp_f32_e32 v94, v93
	v_rcp_f32_e32 v95, v95
	v_add_f32_e32 v92, 1.0, v92
	v_add_f32_e32 v93, 1.0, v101
	v_rcp_f32_e32 v88, v88
	v_rcp_f32_e32 v89, v89
	v_rcp_f32_e32 v92, v92
	v_rcp_f32_e32 v93, v93
	v_pk_fma_f32 v[90:91], v[90:91], 2.0, 1.0 op_sel_hi:[1,0,0] neg_lo:[1,0,0] neg_hi:[1,0,0]
	v_pk_fma_f32 v[94:95], v[94:95], 2.0, 1.0 op_sel_hi:[1,0,0] neg_lo:[1,0,0] neg_hi:[1,0,0]
	v_bfe_u32 v96, v90, 16, 1
	v_bfe_u32 v97, v91, 16, 1
	v_bfe_u32 v101, v94, 16, 1
	v_pk_fma_f32 v[88:89], v[88:89], 2.0, 1.0 op_sel_hi:[1,0,0] neg_lo:[1,0,0] neg_hi:[1,0,0]
	v_pk_fma_f32 v[92:93], v[92:93], 2.0, 1.0 op_sel_hi:[1,0,0] neg_lo:[1,0,0] neg_hi:[1,0,0]
	v_add3_u32 v94, v94, v101, s46
	v_add3_u32 v91, v91, v97, s46
	v_add3_u32 v90, v90, v96, s46
	v_lshrrev_b32_e32 v96, 16, v90
	v_lshrrev_b32_e32 v97, 16, v91
	v_lshrrev_b32_e32 v90, 16, v94
	v_cvt_pk_bf16_f32 v91, v95, v93
	v_bfe_u32 v95, v92, 16, 1
	v_bfe_u32 v101, v89, 16, 1
	v_bfe_u32 v125, v88, 16, 1
	v_add3_u32 v88, v88, v125, s46
	v_add3_u32 v89, v89, v101, s46
	v_add3_u32 v92, v92, v95, s46
	v_and_or_b32 v90, v92, s18, v90
	v_and_or_b32 v89, v89, s18, v97
	v_and_or_b32 v88, v88, s18, v96
	ds_write_b128 v106, v[88:91] offset:16384
	ds_read_b128 v[130:133], v100 offset:35328
	global_load_dwordx4 v[94:97], v[86:87], off offset:64
	global_load_dwordx4 v[90:93], v[86:87], off offset:2048
	s_nop 0
	global_load_dwordx4 v[86:89], v[86:87], off offset:2112
	ds_read_b128 v[134:137], v100 offset:35968
	ds_read_b128 v[138:141], v100 offset:36608
	s_waitcnt lgkmcnt(2)
	v_cndmask_b32_e64 v125, 0, v132, s[10:11]
	v_cndmask_b32_e64 v100, 0, v131, s[10:11]
	v_cndmask_b32_e64 v127, 0, v130, s[10:11]
	v_cndmask_b32_e64 v128, 0, v133, s[10:11]
	ds_read_b128 v[130:133], v99 offset:1024
	ds_read_b128 v[142:145], v99 offset:1040
	s_waitcnt lgkmcnt(2)
	v_cndmask_b32_e32 v146, 0, v139, vcc
	v_cndmask_b32_e32 v99, 0, v138, vcc
	v_lshlrev_b32_e32 v150, 16, v127
	v_lshlrev_b32_e32 v152, 16, v99
	v_lshlrev_b32_e32 v151, 16, v100
	v_lshlrev_b32_e32 v153, 16, v146
	v_pk_add_f32 v[150:151], v[150:151], v[152:153]
	v_lshlrev_b32_e32 v153, 16, v135
	v_lshlrev_b32_e32 v152, 16, v134
	v_pk_fma_f32 v[150:151], v[150:151], 0.5, v[152:153] op_sel_hi:[1,0,1] neg_lo:[0,0,1] neg_hi:[0,0,1]
	s_waitcnt lgkmcnt(1)
	v_mov_b32_e32 v158, v130
	v_mov_b32_e32 v159, v132
	v_pk_fma_f32 v[150:151], v[158:159], v[150:151], v[152:153]
	v_and_b32_e32 v154, 0xffff0000, v127
	v_and_b32_e32 v156, 0xffff0000, v99
	v_and_b32_e32 v155, 0xffff0000, v100
	v_and_b32_e32 v157, 0xffff0000, v146
	v_and_b32_sdwa v99, v151, v213 dst_sel:DWORD dst_unused:UNUSED_PAD src0_sel:WORD_1 src1_sel:DWORD
	v_and_b32_sdwa v100, v150, v213 dst_sel:DWORD dst_unused:UNUSED_PAD src0_sel:WORD_1 src1_sel:DWORD
	v_add3_u32 v100, v150, v100, s46
	v_add3_u32 v99, v151, v99, s46
	v_pk_add_f32 v[150:151], v[154:155], v[156:157]
	v_and_b32_e32 v135, 0xffff0000, v135
	v_and_b32_e32 v134, 0xffff0000, v134
	v_pk_fma_f32 v[150:151], v[150:151], 0.5, v[134:135] op_sel_hi:[1,0,1] neg_lo:[0,0,1] neg_hi:[0,0,1]
	v_mov_b32_e32 v132, v131
	v_pk_fma_f32 v[130:131], v[132:133], v[150:151], v[134:135]
	v_and_b32_e32 v101, 0xffff0000, v128
	v_lshlrev_b32_e32 v147, 16, v128
	v_and_b32_sdwa v128, v130, v213 dst_sel:DWORD dst_unused:UNUSED_PAD src0_sel:WORD_1 src1_sel:DWORD
	v_add3_u32 v128, v130, v128, s46
	v_cndmask_b32_e32 v148, 0, v140, vcc
	v_cndmask_b32_e32 v138, 0, v141, vcc
	v_and_b32_e32 v128, 0xffff0000, v128
	v_and_b32_e32 v139, 0xffff0000, v138
	v_lshlrev_b32_e32 v149, 16, v138
	v_or_b32_sdwa v130, v100, v128 dst_sel:DWORD dst_unused:UNUSED_PAD src0_sel:WORD_1 src1_sel:DWORD
	v_lshlrev_b32_e32 v100, 16, v125
	v_lshlrev_b32_e32 v138, 16, v148
	v_pk_add_f32 v[100:101], v[100:101], v[138:139]
	v_lshlrev_b32_e32 v132, 16, v136
	v_and_b32_e32 v133, 0xffff0000, v137
	s_waitcnt lgkmcnt(0)
	v_mov_b32_e32 v140, v143
	v_and_b32_sdwa v127, v131, v213 dst_sel:DWORD dst_unused:UNUSED_PAD src0_sel:WORD_1 src1_sel:DWORD
	v_and_b32_e32 v146, 0xffff0000, v125
	v_and_b32_e32 v148, 0xffff0000, v148
	v_pk_fma_f32 v[100:101], v[100:101], 0.5, v[132:133] op_sel_hi:[1,0,1] neg_lo:[0,0,1] neg_hi:[0,0,1]
	v_mov_b32_e32 v143, v145
	v_add3_u32 v127, v131, v127, s46
	v_pk_fma_f32 v[100:101], v[100:101], v[142:143], v[132:133]
	v_pk_add_f32 v[132:133], v[146:147], v[148:149]
	v_and_b32_e32 v134, 0xffff0000, v136
	v_lshlrev_b32_e32 v135, 16, v137
	v_mov_b32_e32 v141, v144
	v_and_b32_e32 v127, 0xffff0000, v127
	v_pk_fma_f32 v[132:133], v[132:133], 0.5, v[134:135] op_sel_hi:[1,0,1] neg_lo:[0,0,1] neg_hi:[0,0,1]
	v_or_b32_sdwa v131, v99, v127 dst_sel:DWORD dst_unused:UNUSED_PAD src0_sel:WORD_1 src1_sel:DWORD
	v_pk_fma_f32 v[132:133], v[132:133], v[140:141], v[134:135]
	v_cvt_pk_bf16_f32 v133, v133, v101
	v_and_b32_e32 v99, 15, v98
	v_cvt_pk_bf16_f32 v132, v100, v132
	v_or_b32_e32 v100, s5, v99
	ds_write_b128 v106, v[130:133] offset:24576
	v_and_b32_e32 v101, -16, v98
	v_lshlrev_b32_e32 v100, 7, v100
	s_waitcnt lgkmcnt(0)
	v_add3_u32 v100, 0, v100, v101
	ds_read_b128 v[130:133], v100 offset:16384
	ds_read_b128 v[134:137], v100 offset:16448
	s_waitcnt vmcnt(15) lgkmcnt(1)
	v_mfma_f32_16x16x32_bf16 v[66:69], v[130:133], v[66:69], 0
	s_waitcnt lgkmcnt(0)
	s_waitcnt vmcnt(14) lgkmcnt(0)
	v_mfma_f32_16x16x32_bf16 v[54:57], v[134:137], v[54:57], v[66:69]
	s_nop 5
	v_lshl_add_u32 v66, v99, 2, s7
	v_add_u32_e32 v68, 0x400, v66
	ds_read2_b32 v[66:67], v68 offset0:64 offset1:80
	s_waitcnt vmcnt(9)
	v_mfma_f32_16x16x32_bf16 v[50:53], v[130:133], v[50:53], 0
	v_lshrrev_b32_e32 v69, 2, v98
	v_and_b32_e32 v69, 0x1fffffc, v69
	v_add_lshl_u32 v69, v69, s5, 7
	s_waitcnt lgkmcnt(0)
	v_add_f32_e32 v54, v54, v66
	v_mul_f32_e32 v54, 0xbfb8aa3b, v54
	s_waitcnt vmcnt(8)
	v_mfma_f32_16x16x32_bf16 v[46:49], v[134:137], v[46:49], v[50:53]
	v_exp_f32_e32 v54, v54
	s_nop 1
	v_add_f32_e32 v51, v55, v66
	v_mul_f32_e32 v51, 0xbfb8aa3b, v51
	v_add_f32_e32 v52, v56, v66
	v_exp_f32_e32 v51, v51
	v_mul_f32_e32 v52, 0xbfb8aa3b, v52
	v_exp_f32_e32 v52, v52
	v_mfma_f32_16x16x32_bf16 v[58:61], v[130:133], v[58:61], 0
	v_lshlrev_b32_e32 v50, 1, v99
	v_add3_u32 v69, 0, v69, v50
	v_add_f32_e32 v50, 1.0, v54
	v_rcp_f32_e32 v50, v50
	v_add_f32_e32 v51, 1.0, v51
	v_rcp_f32_e32 v51, v51
	v_add_f32_e32 v52, 1.0, v52
	v_mfma_f32_16x16x32_bf16 v[58:61], v[134:137], v[62:65], v[58:61]
	v_rcp_f32_e32 v52, v52
	v_fma_mixlo_f16 v50, v50, s47, 0
	ds_write_b16 v69, v50 offset:16384
	v_fma_mixlo_f16 v50, v51, s47, 0
	ds_write_b16 v69, v50 offset:16512
	v_fma_mixlo_f16 v50, v52, s47, 0
	v_add_f32_e32 v51, v57, v66
	s_nop 0
	v_add_f32_e32 v52, v58, v67
	v_mul_f32_e32 v51, 0xbfb8aa3b, v51
	v_mul_f32_e32 v52, 0xbfb8aa3b, v52
	v_exp_f32_e32 v51, v51
	v_exp_f32_e32 v52, v52
	ds_write_b16 v69, v50 offset:16640
	v_mfma_f32_16x16x32_bf16 v[62:65], v[130:133], v[74:77], 0
	v_add_f32_e32 v50, 1.0, v51
	v_add_f32_e32 v51, 1.0, v52
	v_add_f32_e32 v52, v59, v67
	v_rcp_f32_e32 v50, v50
	v_mul_f32_e32 v52, 0xbfb8aa3b, v52
	v_rcp_f32_e32 v51, v51
	v_exp_f32_e32 v52, v52
	v_fma_mixlo_f16 v50, v50, s47, 0
	ds_write_b16 v69, v50 offset:16768
	v_fma_mixlo_f16 v50, v51, s47, 0
	v_add_f32_e32 v51, 1.0, v52
	v_add_f32_e32 v52, v60, v67
	v_rcp_f32_e32 v51, v51
	v_mul_f32_e32 v52, 0xbfb8aa3b, v52
	v_exp_f32_e32 v52, v52
	ds_write_b16 v69, v50 offset:16416
	v_fma_mixlo_f16 v50, v51, s47, 0
	ds_write_b16 v69, v50 offset:16544
	v_add_f32_e32 v50, 1.0, v52
	v_rcp_f32_e32 v52, v50
	v_add_f32_e32 v50, v61, v67
	v_mul_f32_e32 v50, 0xbfb8aa3b, v50
	v_exp_f32_e32 v53, v50
	ds_read2_b32 v[50:51], v68 offset0:96 offset1:112
	v_mfma_f32_16x16x32_bf16 v[62:65], v[134:137], v[70:73], v[62:65]
	v_fma_mixlo_f16 v52, v52, s47, 0
	ds_write_b16 v69, v52 offset:16672
	v_add_f32_e32 v52, 1.0, v53
	s_waitcnt lgkmcnt(1)
	v_add_f32_e32 v46, v46, v51
	v_mul_f32_e32 v46, 0xbfb8aa3b, v46
	s_nop 1
	v_add_f32_e32 v53, v62, v50
	v_exp_f32_e32 v46, v46
	v_mul_f32_e32 v53, 0xbfb8aa3b, v53
	v_exp_f32_e32 v53, v53
	v_add_f32_e32 v47, v47, v51
	v_add_f32_e32 v46, 1.0, v46
	v_add_f32_e32 v54, v63, v50
	v_rcp_f32_e32 v46, v46
	v_mul_f32_e32 v47, 0xbfb8aa3b, v47
	v_rcp_f32_e32 v52, v52
	v_mul_f32_e32 v54, 0xbfb8aa3b, v54
	v_add_f32_e32 v53, 1.0, v53
	v_exp_f32_e32 v47, v47
	v_exp_f32_e32 v54, v54
	v_rcp_f32_e32 v53, v53
	v_fma_mixlo_f16 v46, v46, s47, 0
	v_fma_mixlo_f16 v52, v52, s47, 0
	ds_write_b16 v69, v46 offset:16480
	v_add_f32_e32 v46, 1.0, v47
	v_add_f32_e32 v47, v48, v51
	v_add_f32_e32 v54, 1.0, v54
	ds_write_b16 v69, v52 offset:16800
	v_fma_mixlo_f16 v52, v53, s47, 0
	v_add_f32_e32 v53, v64, v50
	v_add_f32_e32 v50, v65, v50
	v_mul_f32_e32 v47, 0xbfb8aa3b, v47
	v_add_f32_e32 v48, v49, v51
	v_rcp_f32_e32 v54, v54
	v_mul_f32_e32 v53, 0xbfb8aa3b, v53
	v_mul_f32_e32 v50, 0xbfb8aa3b, v50
	v_exp_f32_e32 v47, v47
	v_mul_f32_e32 v48, 0xbfb8aa3b, v48
	v_exp_f32_e32 v53, v53
	v_exp_f32_e32 v50, v50
	v_exp_f32_e32 v48, v48
	ds_write_b16 v69, v52 offset:16448
	v_fma_mixlo_f16 v52, v54, s47, 0
	v_rcp_f32_e32 v46, v46
	v_add_f32_e32 v47, 1.0, v47
	ds_write_b16 v69, v52 offset:16576
	v_add_f32_e32 v52, 1.0, v53
	v_add_f32_e32 v50, 1.0, v50
	v_rcp_f32_e32 v47, v47
	v_add_f32_e32 v48, 1.0, v48
	v_rcp_f32_e32 v52, v52
	v_rcp_f32_e32 v50, v50
	v_rcp_f32_e32 v48, v48
	v_fma_mixlo_f16 v46, v46, s47, 0
	ds_write_b16 v69, v46 offset:16608
	v_fma_mixlo_f16 v46, v47, s47, 0
	v_fma_mixlo_f16 v52, v52, s47, 0
	v_fma_mixlo_f16 v50, v50, s47, 0
	ds_write_b16 v69, v46 offset:16736
	v_fma_mixlo_f16 v46, v48, s47, 0
	ds_write_b16 v69, v52 offset:16704
	ds_write_b16 v69, v50 offset:16832
	ds_write_b16 v69, v46 offset:16864
	ds_read_b128 v[46:49], v100 offset:24576
	ds_read_b128 v[50:53], v100 offset:24640
	s_waitcnt vmcnt(4) lgkmcnt(1)
	v_mfma_f32_16x16x32_bf16 v[54:57], v[46:49], v[82:85], 0
	s_waitcnt lgkmcnt(0)
	s_waitcnt lgkmcnt(0)
	v_mfma_f32_16x16x32_bf16 v[34:37], v[50:53], v[34:37], v[54:57]
	s_nop 5
	ds_read2_b32 v[54:55], v68 offset0:128 offset1:144
	v_mfma_f32_16x16x32_bf16 v[38:41], v[46:49], v[38:41], 0
	s_waitcnt lgkmcnt(0)
	v_add_f32_e32 v34, v34, v54
	v_mul_f32_e32 v34, 0xbfb8aa3b, v34
	v_exp_f32_e32 v34, v34
	v_add_f32_e32 v35, v35, v54
	v_mul_f32_e32 v35, 0xbfb8aa3b, v35
	v_exp_f32_e32 v35, v35
	v_add_f32_e32 v34, 1.0, v34
	v_rcp_f32_e32 v34, v34
	v_mfma_f32_16x16x32_bf16 v[38:41], v[50:53], v[42:45], v[38:41]
	v_cvt_f16_f32_e32 v34, v34
	s_waitcnt vmcnt(3)
	v_mfma_f32_16x16x32_bf16 v[42:45], v[46:49], v[78:81], 0
	ds_write_b16 v69, v34 offset:24576
	v_add_f32_e32 v34, 1.0, v35
	v_add_f32_e32 v35, v36, v54
	v_add_f32_e32 v36, v37, v54
	v_mul_f32_e32 v35, 0xbfb8aa3b, v35
	v_mul_f32_e32 v36, 0xbfb8aa3b, v36
	v_exp_f32_e32 v35, v35
	v_exp_f32_e32 v36, v36
	v_rcp_f32_e32 v34, v34
	v_add_f32_e32 v37, v38, v55
	v_add_f32_e32 v35, 1.0, v35
	v_add_f32_e32 v36, 1.0, v36
	v_mul_f32_e32 v37, 0xbfb8aa3b, v37
	v_cvt_f16_f32_e32 v34, v34
	v_rcp_f32_e32 v35, v35
	v_rcp_f32_e32 v36, v36
	v_exp_f32_e32 v37, v37
	ds_write_b16 v69, v34 offset:24704
	v_cvt_f16_f32_e32 v34, v35
	v_cvt_f16_f32_e32 v35, v36
	v_add_f32_e32 v36, 1.0, v37
	v_add_f32_e32 v37, v39, v55
	v_mul_f32_e32 v37, 0xbfb8aa3b, v37
	v_exp_f32_e32 v37, v37
	ds_write_b16 v69, v34 offset:24832
	ds_write_b16 v69, v35 offset:24960
	v_add_f32_e32 v35, v40, v55
	v_mul_f32_e32 v35, 0xbfb8aa3b, v35
	v_add_f32_e32 v34, 1.0, v37
	v_add_f32_e32 v37, v41, v55
	v_rcp_f32_e32 v36, v36
	v_exp_f32_e32 v35, v35
	v_mul_f32_e32 v37, 0xbfb8aa3b, v37
	v_exp_f32_e32 v37, v37
	v_cvt_f16_f32_e32 v36, v36
	v_rcp_f32_e32 v38, v34
	v_add_f32_e32 v34, 1.0, v35
	v_rcp_f32_e32 v39, v34
	v_add_f32_e32 v34, 1.0, v37
	v_rcp_f32_e32 v37, v34
	ds_read2_b32 v[34:35], v68 offset0:160 offset1:176
	s_waitcnt vmcnt(2)
	v_mfma_f32_16x16x32_bf16 v[42:45], v[50:53], v[94:97], v[42:45]
	ds_write_b16 v69, v36 offset:24608
	v_cvt_f16_f32_e32 v36, v38
	v_cvt_f16_f32_e32 v38, v39
	v_cvt_f16_f32_e32 v37, v37
	ds_write_b16 v69, v36 offset:24736
	ds_write_b16 v69, v38 offset:24864
	ds_write_b16 v69, v37 offset:24992
	s_waitcnt lgkmcnt(4)
	v_add_f32_e32 v39, v42, v34
	v_mul_f32_e32 v39, 0xbfb8aa3b, v39
	v_add_f32_e32 v37, v43, v34
	v_exp_f32_e32 v39, v39
	v_mul_f32_e32 v37, 0xbfb8aa3b, v37
	v_add_f32_e32 v38, v44, v34
	v_exp_f32_e32 v37, v37
	v_mul_f32_e32 v38, 0xbfb8aa3b, v38
	v_exp_f32_e32 v38, v38
	v_add_f32_e32 v36, 1.0, v39
	v_add_f32_e32 v34, v45, v34
	s_waitcnt vmcnt(1)
	v_mfma_f32_16x16x32_bf16 v[46:49], v[46:49], v[90:93], 0
	v_rcp_f32_e32 v36, v36
	v_add_f32_e32 v37, 1.0, v37
	v_mul_f32_e32 v34, 0xbfb8aa3b, v34
	v_rcp_f32_e32 v37, v37
	v_add_f32_e32 v38, 1.0, v38
	v_exp_f32_e32 v34, v34
	v_rcp_f32_e32 v38, v38
	s_waitcnt vmcnt(0)
	v_mfma_f32_16x16x32_bf16 v[46:49], v[50:53], v[86:89], v[46:49]
	v_cvt_f16_f32_e32 v36, v36
	v_cvt_f16_f32_e32 v37, v37
	v_add_f32_e32 v34, 1.0, v34
	v_cvt_f16_f32_e32 v38, v38
	v_rcp_f32_e32 v34, v34
	ds_write_b16 v69, v36 offset:24640
	ds_write_b16 v69, v37 offset:24768
	ds_write_b16 v69, v38 offset:24896
	v_add_f32_e32 v36, v46, v35
	v_add_f32_e32 v37, v47, v35
	v_mul_f32_e32 v36, 0xbfb8aa3b, v36
	v_mul_f32_e32 v37, 0xbfb8aa3b, v37
	v_cvt_f16_f32_e32 v34, v34
	v_exp_f32_e32 v36, v36
	v_exp_f32_e32 v37, v37
	ds_write_b16 v69, v34 offset:25024
	v_add_f32_e32 v34, 1.0, v36
	v_add_f32_e32 v36, 1.0, v37
	v_add_f32_e32 v37, v48, v35
	v_mul_f32_e32 v37, 0xbfb8aa3b, v37
	v_add_f32_e32 v35, v49, v35
	v_exp_f32_e32 v37, v37
	v_mul_f32_e32 v35, 0xbfb8aa3b, v35
	v_exp_f32_e32 v35, v35
	v_rcp_f32_e32 v34, v34
	v_rcp_f32_e32 v36, v36
	v_add_f32_e32 v37, 1.0, v37
	v_rcp_f32_e32 v37, v37
	v_add_f32_e32 v35, 1.0, v35
	v_rcp_f32_e32 v35, v35
	v_cvt_f16_f32_e32 v34, v34
	v_cvt_f16_f32_e32 v36, v36
	v_cvt_f16_f32_e32 v37, v37
	v_cvt_f16_f32_e32 v35, v35
	ds_write_b16 v69, v34 offset:24672
	ds_write_b16 v69, v36 offset:24800
	ds_write_b16 v69, v37 offset:24928
	ds_write_b16 v69, v35 offset:25056

.LBB0_382:
	s_andn2_b64 vcc, exec, s[10:11]
	s_cbranch_vccnz .LBB0_454
	s_and_b64 s[10:11], s[12:13], exec
	s_cselect_b32 s10, 4, 2
	s_lshr_b32 s5, s0, 7
	s_lshl_b32 s7, s5, 12
	s_lshl_b32 s3, s1, 3
	s_add_i32 s33, s74, -1
	s_add_i32 s75, s7, 0
	s_bfe_u32 s11, s0, 0x10006
	s_bitcmp1_b32 s0, 6
	s_cselect_b64 s[88:89], -1, 0
	s_and_b32 s0, s0, 0x3fffff80
	s_lshl_b32 s0, s0, 2
	s_add_i32 s62, s0, 0
	s_lshl_b32 s0, s1, 12
	s_add_i32 s7, s0, 0
	s_lshl_b32 s0, s1, 10
	s_lshl_b32 s77, s5, 10
	s_add_i32 s0, s0, 0
	s_lshl_b32 s5, s1, 11
	s_add_i32 s44, s0, 0x1e800
	s_add_i32 s51, s0, 0x1a800
	s_add_i32 s5, s5, 0
	s_add_i32 s18, s0, 0x1b800
	s_add_i32 s12, s1, -4
	s_lshl_b32 s0, s30, 16
	s_lshl_b32 s13, s56, 12
	s_add_i32 s76, s75, 0x14800
	s_add_i32 s62, s62, 0x1f800
	s_add_i32 s63, s74, 0xffffff80
	s_lshl_b32 s59, s56, 6
	s_add_i32 s5, s5, 0x1c800
	s_or_b32 s14, s13, s0
	s_lshl_b32 s13, s12, 1
	s_add_i32 s71, s74, -8
	s_lshl_b32 s0, s12, 4
	s_cmp_lt_u32 s1, s10
	s_cselect_b64 s[90:91], -1, 0
	s_lshl_b32 s12, s12, 11
	v_readlane_b32 s16, v255, 29
	s_add_i32 s34, s12, 0
	s_or_b32 s12, s13, 1
	v_readlane_b32 s17, v255, 30
	s_lshl_b32 s60, s12, 3
	s_lshl_b32 s12, s12, 10
	s_lshl_b32 s10, s11, 10
	s_lshl_b32 s35, s1, 5
	s_lshl_b32 s15, s30, 11
	s_lshl_b32 s11, s11, 5
	s_nor_b64 s[92:93], s[82:83], s[16:17]
	s_add_i32 s61, s12, 0
	s_lshl_b32 s12, s56, 3
	v_readlane_b32 s13, v255, 23
	s_add_u32 s12, s13, s12
	v_readlane_b32 s13, v255, 24
	s_addc_u32 s13, s13, 0
	s_lshl_b32 s16, s30, 2
	s_add_u32 s94, s12, s16
	s_addc_u32 s95, s13, 0
	s_lshl_b32 s12, s30, 7
	s_add_u32 s96, s54, s12
	s_addc_u32 s97, s55, 0
	s_lshl_b32 s12, s56, 7
	s_add_u32 s54, s36, s12
	s_addc_u32 s55, s37, 0
	s_add_u32 s52, s52, s12
	s_addc_u32 s53, s53, 0
	s_add_u32 s12, s42, s12
	s_addc_u32 s13, s43, 0
	s_add_i32 s15, s81, s15
	s_add_i32 s15, s15, s31
	v_writelane_b32 v255, s56, 59
	s_mov_b32 s42, s18
	s_add_i32 s66, s48, s33
	s_add_i32 s67, s15, 0x800
	s_or_b32 s70, s10, 0x18800
	s_lshl_b32 s30, s14, 1
	s_lshl_b32 s72, s11, 1
	v_readlane_b32 s10, v255, 25
	v_readlane_b32 s11, v255, 26
	v_lshlrev_b32_e32 v34, 7, v1
	v_lshrrev_b32_e32 v36, 1, v1
	v_and_b32_e32 v34, 0x780, v34
	v_and_b32_e32 v36, -8, v36
	v_mov_b32_e32 v35, 0
	v_lshl_add_u32 v34, v36, 1, v34
	s_lshr_b32 s12, s1, 2
	s_lshl_b32 s12, s12, 18
	s_and_b32 s13, s1, 3
	s_lshl_b32 s13, s13, 11
	s_add_i32 s12, s12, s13
	s_add_i32 s12, s12, s30
	s_mov_b32 s13, 0
	v_lshl_add_u64 v[36:37], s[10:11], 0, v[34:35]
	v_lshl_add_u64 v[36:37], v[36:37], 0, s[12:13]
	s_lshl_b32 s12, s1, 11
	s_add_i32 s12, s12, 0x24000
	s_mov_b32 s13, m0
	s_mov_b32 m0, s12
	s_nop 0
	global_load_lds_dwordx4 v[36:37], off
	s_add_i32 s12, s12, 0x3c0
	s_mov_b32 m0, s12
	s_nop 0
	global_load_lds_dwordx4 v[36:37], off offset:64
	s_mov_b32 m0, s13
	s_branch .LBB0_385
